# inproj ticket order: consecutive tickets share the A (activation) tile instead of the weight tile
# speedup vs baseline: 1.0050x; 1.0048x over previous
;   __device__ __forceinline__ const float* x() const { return (const float*)(const __attribute__((address_space(1))) float*)kp[0]; }
;   __device__ __forceinline__ half_t* xh() const { return (half_t*)(ws() + OFF_xh); }
;   __device__ __forceinline__ half_t* winT() const { return (half_t*)(ws() + OFF_winT); }
; __device__ __forceinline__ int orig_col(int n) {
;   if (n < 1536) return n;
;   if (n < 2048) return 1664 + (n - 1536);
;   if (n < 2560) return 2472 + (n - 2048);
;   if (n < 3072) return 3776 + (n - 2560);
;   if (n < 6144) return 4288 + (n - 3072);
;   if (n < 6400) return 2176 + (n - 6144);
;   if (n < 7168) return 2984 + (n - 6400);
;   if (n < 7296) return 1536 + (n - 7168);
;   if (n < 7328) return 2432 + (n - 7296);
;   if (n < 7336) return 2464 + (n - 7328);
;   if (n < 7360) return 3752 + (n - 7336);
;   return -1;
; __device__ __forceinline__ void phase_inproj(const KP& p, int l, char* smem, int* q, int xcc) {
;     ...
;     const int mt = (grp & 15) * 4 + (within & 3), nt = (grp >> 4) * 8 + (within >> 2);
;     if (nt >= 58) return;
;     const int m0 = mt * 256, n0 = nt * 128;
;     const half_t* A = p.xh() + (size_t)m0 * DM;
;     const half_t* B = p.winT() + (size_t)n0 * DM;
;     int tidx = threadIdx.x;
;     asm volatile("" : "+v"(tidx));
;     const int lane = tidx & 63, wn = (tidx >> 6) & 1;
;     float bv[2];
; #pragma unroll
;     for (int ni = 0; ni < 2; ++ni) {
;       const int oc = orig_col(n0 + wn * 64 + ni * 32 + (lane & 31));
;       bv[ni] = oc >= 0 ? bias[oc] : 0.f;
.LBB0_197:
	s_andn2_b64 vcc, exec, s[2:3]
	s_cbranch_vccnz .LBB0_188
	s_lshl_b32 s53, s15, 5
	s_sub_i32 s43, s14, s53
	s_lshl_b32 s2, s15, 2
	s_and_b32 s38, s2, -8
	s_and_b32 s2, s43, 7
	s_add_i32 s38, s38, s2
	s_cmp_gt_i32 s38, 57
	s_cbranch_scc1 .LBB0_188
	s_cmp_eq_u32 s38, 57
	s_cselect_b32 s2, 1, 0
	v_writelane_b32 v251, s2, 22
	v_mov_b32_e32 v0, v224
	s_lshl_b32 s18, s38, 7
	v_and_b32_e32 v0, 0x5f, v0
	v_or_b32_e32 v2, s18, v0
	s_ashr_i32 s19, s18, 31
	v_cmp_lt_i32_e32 vcc, s60, v2
	v_mov_b32_e32 v0, v2
	s_and_saveexec_b64 s[2:3], vcc
	s_cbranch_execz .LBB0_236
	s_cmpk_gt_u32 s18, 0x7ff
	s_mov_b64 s[14:15], -1
	s_cbranch_scc0 .LBB0_234
	s_cmpk_gt_u32 s18, 0x9ff
	s_cbranch_scc0 .LBB0_231
	s_cmpk_gt_u32 s18, 0xbff
	s_cbranch_scc0 .LBB0_228
	s_cmpk_gt_u32 s18, 0x17ff
	s_cbranch_scc0 .LBB0_225
	s_cmpk_gt_u32 s18, 0x18ff
	s_cbranch_scc0 .LBB0_222
	s_cmpk_gt_u32 s18, 0x1bff
	s_cbranch_scc0 .LBB0_219
	s_cmpk_gt_u32 s18, 0x1c7f
	s_cbranch_scc0 .LBB0_216
	s_movk_i32 s14, 0x1c9f
	v_cmp_lt_u32_e32 vcc, s14, v2
	s_and_saveexec_b64 s[14:15], vcc
	s_xor_b64 s[30:31], exec, s[14:15]
	s_cbranch_execz .LBB0_213
	s_movk_i32 s14, 0x1ca7
	v_cmp_lt_u32_e32 vcc, s14, v2
	s_and_saveexec_b64 s[14:15], vcc
	s_xor_b64 s[14:15], exec, s[14:15]
	s_movk_i32 s39, 0x1cc0
	v_add_u32_e32 v0, 0xfffff200, v2
	v_cmp_gt_u32_e32 vcc, s39, v2
	s_nop 1
	v_cndmask_b32_e32 v0, -1, v0, vcc
	s_andn2_saveexec_b64 s[14:15], s[14:15]
	v_add_u32_e32 v0, 0xffffed00, v2
	s_or_b64 exec, exec, s[14:15]

;   __device__ __forceinline__ const float* x() const { return (const float*)(const __attribute__((address_space(1))) float*)kp[0]; }
;   __device__ __forceinline__ half_t* xh() const { return (half_t*)(ws() + OFF_xh); }
;   __device__ __forceinline__ half_t* winT() const { return (half_t*)(ws() + OFF_winT); }
;   __device__ __forceinline__ half_t* vsT() const { return (half_t*)(ws() + OFF_vsT); }
;   __device__ __forceinline__ half_t* vwT() const { return (half_t*)(ws() + OFF_vwT); }
; template <class LA, class LB, class EP>
; __device__ __forceinline__ void gemm_tile_big(int K, LA loadA, LB loadB, EP epi, char* smem) {
;   half_t* sA = (half_t*)smem;
;   half_t* sB = sA + 256 * 72;
;   int tid = threadIdx.x;
;   asm volatile("" : "+v"(tid));
;   const int lane = tid & 63, wid = tid >> 6;
;   const int wm = wid >> 1, wn = wid & 1;
;   f32x16 acc[4][2];
; #pragma unroll
;   for (int i = 0; i < 4; ++i)
; #pragma unroll
;     for (int j = 0; j < 2; ++j)
; #pragma unroll
;       for (int r = 0; r < 16; ++r) acc[i][j][r] = 0.f;
;   const int lr = tid >> 3, lc = (tid & 7) * 8;
;   uint4 ra[8], rb[4];
; #pragma unroll
;   for (int i = 0; i < 8; ++i) ra[i] = loadA(lr + 32 * i, lc);
; #pragma unroll
;   for (int i = 0; i < 4; ++i) rb[i] = loadB(lr + 32 * i, lc);
; __device__ __forceinline__ void phase_inproj(const KP& p, int l, char* smem, int* q, int xcc) {
;     ...
;     const int mt = (grp & 15) * 4 + (within & 3), nt = (grp >> 4) * 8 + (within >> 2);
;     if (nt >= 58) return;
;     const int m0 = mt * 256, n0 = nt * 128;
;     const half_t* A = p.xh() + (size_t)m0 * DM;
;     const half_t* B = p.winT() + (size_t)n0 * DM;
;     int tidx = threadIdx.x;
;     asm volatile("" : "+v"(tidx));
;     const int lane = tidx & 63, wn = (tidx >> 6) & 1;
;     float bv[2];
; #pragma unroll
;     for (int ni = 0; ni < 2; ++ni) {
;       const int oc = orig_col(n0 + wn * 64 + ni * 32 + (lane & 31));
;       bv[ni] = oc >= 0 ? bias[oc] : 0.f;
;     }
;     half_t* vT = (nt == 53) ? p.vsT() : ((nt == 55) ? p.vwT() : nullptr);
;     gemm_tile_big(
;         DM, [&](int r, int k) { return *(const uint4*)(A + (size_t)r * DM + k); },
;         [&](int r, int k) { return *(const uint4*)(B + (size_t)r * DM + k); },
.LBB0_285:
	s_lshl_b32 s2, s42, 2
	s_and_b32 s2, s2, 60
	s_lshr_b32 s15, s43, 3
	s_or_b32 s14, s2, s15
	v_mov_b32_e32 v194, v224
	s_lshl_b32 s30, s14, 19
	s_lshl_b64 s[2:3], s[18:19], 11
	s_add_u32 s30, s8, s30
	v_ashrrev_i32_e32 v2, 3, v194
	v_lshlrev_b32_e32 v0, 3, v194
	v_and_b32_e32 v20, 56, v0
	v_ashrrev_i32_e32 v3, 31, v2
	s_addc_u32 s31, s44, 0
	v_lshlrev_b32_e32 v0, 1, v20
	v_lshlrev_b64 v[6:7], 11, v[2:3]
	v_lshl_add_u64 v[4:5], s[30:31], 0, v[0:1]
	v_lshl_add_u64 v[10:11], v[6:7], 0, s[20:21]
	v_lshl_add_u64 v[8:9], v[4:5], 0, v[6:7]
	v_lshl_add_u64 v[12:13], v[4:5], 0, v[10:11]
	v_lshl_add_u64 v[12:13], v[6:7], 0, s[80:81]
	v_lshl_add_u64 v[14:15], v[4:5], 0, v[12:13]
	v_lshl_add_u64 v[16:17], v[6:7], 0, s[82:83]
	v_lshl_add_u64 v[18:19], v[4:5], 0, v[16:17]
	v_add_u32_e32 v14, 0x80, v2
	v_ashrrev_i32_e32 v15, 31, v14
	v_lshlrev_b64 v[18:19], 11, v[14:15]
	v_lshl_add_u64 v[4:5], v[4:5], 0, v[18:19]
	v_add_co_u32_e32 v18, vcc, s61, v8
	s_add_u32 s42, s45, s2
	s_nop 0
	v_addc_co_u32_e32 v19, vcc, 0, v9, vcc
	v_add_co_u32_e32 v4, vcc, s64, v8
	s_addc_u32 s43, s46, s3
	s_nop 0
	v_addc_co_u32_e32 v5, vcc, 0, v9, vcc
	v_add_co_u32_e32 v8, vcc, s65, v8
	v_and_b32_e32 v3, 0xfffff9f, v194
	s_nop 0
	v_addc_co_u32_e32 v9, vcc, 0, v9, vcc
	v_lshl_add_u64 v[4:5], s[42:43], 0, v[0:1]
	v_lshl_add_u64 v[8:9], v[4:5], 0, v[6:7]
	v_lshl_add_u64 v[10:11], v[4:5], 0, v[10:11]
	v_lshl_add_u64 v[8:9], v[4:5], 0, v[12:13]
	v_lshl_add_u64 v[4:5], v[4:5], 0, v[16:17]
	v_lshrrev_b32_e32 v4, 1, v194
	v_and_b32_e32 v4, 16, v4
	v_mul_lo_u32 v2, v2, s37
	v_bfe_u32 v247, v194, 6, 1
	v_and_b32_e32 v195, 31, v194
	v_mad_u64_u32 v[178:179], s[30:31], v3, s36, v[4:5]
	v_add_lshl_u32 v196, v2, v20, 1
	v_lshl_add_u64 v[2:3], v[6:7], 0, s[2:3]
	s_add_i32 s2, s52, s53
	v_lshl_or_b32 v249, v247, 6, v195
	v_mad_u64_u32 v[188:189], s[30:31], v14, s36, v[0:1]
	v_or_b32_e32 v0, 0x60, v194
	s_lshl_b32 s2, s2, 19
	v_mad_u64_u32 v[180:181], s[30:31], v0, s36, v[4:5]
	v_mad_u32_u24 v179, v249, s36, v4
	v_lshlrev_b32_e32 v4, 4, v194
	s_and_b32 s2, s2, 0x1e00000
	s_lshl_b32 s3, s15, 19
	v_and_b32_e32 v4, 0x70, v4
	s_or_b32 s2, s2, s3
	v_or_b32_e32 v2, v2, v4
	s_add_u32 s2, s0, s2
	v_lshl_add_u64 v[190:191], s[0:1], 0, v[2:3]
	v_or_b32_e32 v6, v6, v4
	s_addc_u32 s3, s1, 0
	v_mov_b32_e32 v2, 0
	v_add_u32_e32 v198, 0x1200, v188
	v_add_u32_e32 v197, 0x2400, v188
	v_add_u32_e32 v189, 0x3600, v188
	v_add_u32_e32 v0, 0x1200, v179
	v_lshl_add_u64 v[192:193], s[2:3], 0, v[6:7]
	v_mov_b32_e32 v3, v2
	v_mov_b32_e32 v4, v2
	v_mov_b32_e32 v5, v2
	v_mov_b32_e32 v6, v2
	v_mov_b32_e32 v7, v2
	v_mov_b32_e32 v8, v2
	v_mov_b32_e32 v9, v2
	v_mov_b32_e32 v10, v2
	v_mov_b32_e32 v11, v2
	v_mov_b32_e32 v12, v2
	v_mov_b32_e32 v13, v2
	v_mov_b32_e32 v14, v2
	v_mov_b32_e32 v15, v2
	v_mov_b32_e32 v16, v2
	v_mov_b32_e32 v17, v2
	v_mov_b32_e32 v18, v2
	v_mov_b32_e32 v19, v2
	v_mov_b32_e32 v20, v2
	v_mov_b32_e32 v21, v2
	v_mov_b32_e32 v22, v2
	v_mov_b32_e32 v23, v2
	v_mov_b32_e32 v24, v2
	v_mov_b32_e32 v25, v2
	v_mov_b32_e32 v26, v2
	v_mov_b32_e32 v27, v2
	v_mov_b32_e32 v28, v2
	v_mov_b32_e32 v29, v2
	v_mov_b32_e32 v30, v2
	v_mov_b32_e32 v31, v2
	v_mov_b32_e32 v32, v2
	v_mov_b32_e32 v33, v2
	v_mov_b32_e32 v34, v2
	v_mov_b32_e32 v35, v2
	v_mov_b32_e32 v36, v2
	v_mov_b32_e32 v37, v2
	v_mov_b32_e32 v38, v2
	v_mov_b32_e32 v39, v2
	v_mov_b32_e32 v40, v2
	v_mov_b32_e32 v41, v2
	v_mov_b32_e32 v42, v2
	v_mov_b32_e32 v43, v2
	v_mov_b32_e32 v44, v2
	v_mov_b32_e32 v45, v2
	v_mov_b32_e32 v46, v2
	v_mov_b32_e32 v47, v2
	v_mov_b32_e32 v48, v2
	v_mov_b32_e32 v49, v2
	v_mov_b32_e32 v50, v2
	v_mov_b32_e32 v51, v2
	v_mov_b32_e32 v52, v2
	v_mov_b32_e32 v53, v2
	v_mov_b32_e32 v54, v2
	v_mov_b32_e32 v55, v2
	v_mov_b32_e32 v56, v2
	v_mov_b32_e32 v57, v2
	v_mov_b32_e32 v58, v2
	v_mov_b32_e32 v59, v2
	v_mov_b32_e32 v60, v2
	v_mov_b32_e32 v61, v2
	v_mov_b32_e32 v62, v2
	v_mov_b32_e32 v63, v2
	v_mov_b32_e32 v64, v2
	v_mov_b32_e32 v65, v2
	v_mov_b32_e32 v66, v2
	v_mov_b32_e32 v67, v2
	v_mov_b32_e32 v68, v2
	v_mov_b32_e32 v69, v2
	v_mov_b32_e32 v70, v2
	v_mov_b32_e32 v71, v2
	v_mov_b32_e32 v72, v2
	v_mov_b32_e32 v73, v2
	v_mov_b32_e32 v74, v2
	v_mov_b32_e32 v75, v2
	v_mov_b32_e32 v76, v2
	v_mov_b32_e32 v77, v2
	v_mov_b32_e32 v78, v2
	v_mov_b32_e32 v79, v2
	v_mov_b32_e32 v80, v2
	v_mov_b32_e32 v81, v2
	v_mov_b32_e32 v82, v2
	v_mov_b32_e32 v83, v2
	v_mov_b32_e32 v84, v2
	v_mov_b32_e32 v85, v2
	v_mov_b32_e32 v86, v2
	v_mov_b32_e32 v87, v2
	v_mov_b32_e32 v88, v2
	v_mov_b32_e32 v89, v2
	v_mov_b32_e32 v90, v2
	v_mov_b32_e32 v91, v2
	v_mov_b32_e32 v92, v2
	v_mov_b32_e32 v93, v2
	v_mov_b32_e32 v94, v2
	v_mov_b32_e32 v95, v2
	v_mov_b32_e32 v96, v2
	v_mov_b32_e32 v97, v2
	v_mov_b32_e32 v98, v2
	v_mov_b32_e32 v99, v2
	v_mov_b32_e32 v100, v2
	v_mov_b32_e32 v101, v2
	v_mov_b32_e32 v102, v2
	v_mov_b32_e32 v103, v2
	v_mov_b32_e32 v104, v2
	v_mov_b32_e32 v105, v2
	v_mov_b32_e32 v106, v2
	v_mov_b32_e32 v107, v2
	v_mov_b32_e32 v108, v2
	v_mov_b32_e32 v109, v2
	v_mov_b32_e32 v110, v2
	v_mov_b32_e32 v111, v2
	v_mov_b32_e32 v112, v2
	v_mov_b32_e32 v113, v2
	v_mov_b32_e32 v114, v2
	v_mov_b32_e32 v115, v2
	v_mov_b32_e32 v116, v2
	v_mov_b32_e32 v117, v2
	v_mov_b32_e32 v118, v2
	v_mov_b32_e32 v119, v2
	v_mov_b32_e32 v120, v2
	v_mov_b32_e32 v121, v2
	v_mov_b32_e32 v122, v2
	v_mov_b32_e32 v123, v2
	v_mov_b32_e32 v124, v2
	v_mov_b32_e32 v125, v2
	v_mov_b32_e32 v126, v2
	v_mov_b32_e32 v127, v2
	v_mov_b32_e32 v128, v2
	v_mov_b32_e32 v129, v2
	v_lshrrev_b32_e32 v208, 2, v194
	v_and_b32_e32 v209, 3, v194
	v_lshlrev_b32_e32 v210, 11, v208
	v_mul_u32_u24_e32 v196, 0x50, v208
	v_lshl_add_u32 v196, v209, 4, v196
	v_lshlrev_b32_e32 v208, 4, v194
	v_add_u32_e32 v209, 0x1000, v208
	v_add_u32_e32 v210, 0x2000, v208
	v_add_u32_e32 v211, 0x3000, v208
	v_lshrrev_b32_e32 v178, 7, v194
	v_and_b32_e32 v179, 31, v194
	v_lshl_or_b32 v178, v178, 7, v179
	v_mul_u32_u24_e32 v178, 0x50, v178
	v_bfe_u32 v212, v194, 5, 1
	v_lshl_add_u32 v178, v212, 4, v178
	v_bfe_u32 v213, v194, 6, 1
	v_lshl_or_b32 v179, v213, 6, v179
	v_mul_u32_u24_e32 v179, 0x50, v179
	v_lshl_add_u32 v179, v212, 4, v179
	s_lshl_b32 s38, s14, 14
	s_add_u32 s38, s8, s38
	s_addc_u32 s39, s44, 0
	s_lshl_b64 s[2:3], s[18:19], 6
	s_add_u32 s2, s45, s2
	s_addc_u32 s3, s46, s3
	global_load_dwordx4 v[130:133], v208, s[38:39] sc1
	global_load_dwordx4 v[134:137], v209, s[38:39] sc1
	global_load_dwordx4 v[138:141], v210, s[38:39] sc1
	global_load_dwordx4 v[142:145], v211, s[38:39] sc1
	global_load_dwordx4 v[146:149], v208, s[2:3] sc1
	global_load_dwordx4 v[150:153], v209, s[2:3] sc1
	s_add_u32 s38, s38, 0x100000
	s_addc_u32 s39, s39, 0
	s_add_u32 s2, s2, 0x74000
	s_addc_u32 s3, s3, 0
	global_load_dwordx4 v[154:157], v208, s[38:39] sc1
	global_load_dwordx4 v[158:161], v209, s[38:39] sc1
	global_load_dwordx4 v[162:165], v210, s[38:39] sc1
	global_load_dwordx4 v[166:169], v211, s[38:39] sc1
	global_load_dwordx4 v[170:173], v208, s[2:3] sc1
	global_load_dwordx4 v[174:177], v209, s[2:3] sc1
	s_add_u32 s38, s38, 0x100000
	s_addc_u32 s39, s39, 0
	s_add_u32 s2, s2, 0x74000
	s_addc_u32 s3, s3, 0
	s_barrier
; template <class LA, class LB, class EP>
; __device__ __forceinline__ void gemm_tile_big(int K, LA loadA, LB loadB, EP epi, char* smem) {
;     ...
;   for (int kt = 0; kt < nk; ++kt) {
;     __syncthreads();
; #pragma unroll
;     for (int i = 0; i < 8; ++i) *(uint4*)&sA[(lr + 32 * i) * 72 + lc] = ra[i];
; #pragma unroll
;     for (int i = 0; i < 4; ++i) *(uint4*)&sB[(lr + 32 * i) * 72 + lc] = rb[i];
;     __syncthreads();
	s_waitcnt vmcnt(11)
	ds_write_b128 v196, v[130:133]
	s_waitcnt vmcnt(10)
	ds_write_b128 v196, v[134:137] offset:5120
	s_waitcnt vmcnt(9)
	ds_write_b128 v196, v[138:141] offset:10240
	s_waitcnt vmcnt(8)
	ds_write_b128 v196, v[142:145] offset:15360
	s_waitcnt vmcnt(7)
	ds_write_b128 v196, v[146:149] offset:20480
	s_waitcnt vmcnt(6)
	ds_write_b128 v196, v[150:153] offset:25600
	s_waitcnt lgkmcnt(0)
	s_barrier
	s_mov_b32 s30, 0
